# removes every s_setprio from the GEMM main loop (priority flips were not load-bearing here), on top of the v65 stack
# speedup vs baseline: 1.0109x; 1.0109x over previous
; #define PG8_STAGE(bufoff, gbase, voff) do { _Pragma("unroll") for (int _i = 0; _i < 2; ++_i) \
;         __builtin_amdgcn_global_load_lds((const unsigned*)((const char*)(gbase) + (voff)[_i]), (LAS unsigned*)(lds + (bufoff) + ldsw + _i * 8192), 16, 0, 0); } while (0)
; #define PG8_LDA(dst, b, h) do { _Pragma("unroll") for (int m = 0; m < 4; ++m) _Pragma("unroll") for (int k = 0; k < 2; ++k) dst[m][k] = *(const LAS bf16x8*)(lds + PG8_SA(b, h) + aoff + m * 2048 + k * 1024); } while (0)
; #define PG8_LDB(dst, b, h) do { _Pragma("unroll") for (int n = 0; n < 2; ++n) _Pragma("unroll") for (int k = 0; k < 2; ++k) dst[n][k] = *(const LAS bf16x8*)(lds + PG8_SB(b, h) + boff + n * 2048 + k * 1024); } while (0)
; #define PG8_MMA(ai, bj, At, Bt) do { __builtin_amdgcn_s_setprio(1); _Pragma("unroll") for (int m = 0; m < 4; ++m) _Pragma("unroll") for (int n = 0; n < 2; ++n) _Pragma("unroll") for (int k = 0; k < 2; ++k) \
;         acc[ai][bj][m][n] = __builtin_amdgcn_mfma_f32_16x16x32_bf16(Bt[n][k], At[m][k], acc[ai][bj][m][n], 0, 0, 0); __builtin_amdgcn_s_setprio(0); } while (0)
; #define PG8_WAIT_V(n) asm volatile("s_waitcnt vmcnt(" #n ")" ::: "memory")
; #define PG8_WAIT_L(n) asm volatile("s_waitcnt lgkmcnt(" #n ")" ::: "memory")
; #define PG8_BAR __builtin_amdgcn_s_barrier()
; #define PG8_SCHED __builtin_amdgcn_sched_barrier(0)
; __device__ __forceinline__ void gemm_phase(LAS unsigned char* lds, const Gemm g, const StaticOrder& S, const Epi& E) {
;     ...
;             PG8_LDB(B0, 0, 0); PG8_LDB(B1, 0, 1); PG8_SCHED; PG8_LDA(At, 0, 0); PG8_STAGE(PG8_SA(1, 1), a1 + hstepA, voffA);
;             PG8_WAIT_V(8); PG8_WAIT_L(0); PG8_BAR; PG8_MMA(0, 0, At, B0); PG8_MMA(0, 1, At, B1); PG8_BAR; PG8_SCHED;
;             PG8_LDA(At, 0, 1); PG8_STAGE(PG8_SB(0, 0), b2, voffB); PG8_STAGE(PG8_SB(0, 1), b2 + hstepB, voffB); PG8_STAGE(PG8_SA(0, 0), a2, voffA);
;             PG8_WAIT_V(8); PG8_WAIT_L(0); PG8_BAR; PG8_MMA(1, 0, At, B0); PG8_MMA(1, 1, At, B1); PG8_BAR; PG8_SCHED;
.LBB0_177:
	s_waitcnt lgkmcnt(0)
	ds_read_b128 v[130:133], v226
	ds_read_b128 v[134:137], v226 offset:1024
	ds_read_b128 v[138:141], v226 offset:2048
	ds_read_b128 v[142:145], v226 offset:3072
	ds_read_b128 v[146:149], v227
	ds_read_b128 v[150:153], v227 offset:1024
	ds_read_b128 v[154:157], v227 offset:2048
	ds_read_b128 v[182:185], v227 offset:3072
	s_add_i32 s27, s17, 2
	s_add_u32 s2, s0, 0x80
	s_addc_u32 s3, s1, 0
	s_cmp_eq_u32 s85, s17
	s_cselect_b32 s3, s7, s3
	s_cselect_b32 s2, s6, s2
	s_cselect_b32 s41, s95, s16
	s_cselect_b32 s40, s94, s5
	s_add_i32 m0, s71, 0xc000
	ds_read_b128 v[186:189], v217
	ds_read_b128 v[190:193], v217 offset:1024
	ds_read_b128 v[194:197], v217 offset:2048
	ds_read_b128 v[198:201], v217 offset:3072
	ds_read_b128 v[202:205], v217 offset:4096
	ds_read_b128 v[206:209], v217 offset:5120
	ds_read_b128 v[218:221], v217 offset:6144
	ds_read_b128 v[222:225], v217 offset:7168
	global_load_lds_dwordx4 v178, s[0:1]
	s_add_i32 m0, s71, 0xe000
	s_nop 0
	global_load_lds_dwordx4 v180, s[0:1]
	s_waitcnt vmcnt(8)
	s_waitcnt lgkmcnt(0)
	s_barrier
	v_mfma_f32_16x16x32_bf16 v[114:117], v[130:133], v[186:189], v[114:117]
	v_mfma_f32_16x16x32_bf16 v[126:129], v[138:141], v[186:189], v[126:129]
	v_mfma_f32_16x16x32_bf16 v[110:113], v[130:133], v[194:197], v[110:113]
	v_mfma_f32_16x16x32_bf16 v[102:105], v[138:141], v[194:197], v[102:105]
	v_mfma_f32_16x16x32_bf16 v[94:97], v[130:133], v[202:205], v[94:97]
	v_mfma_f32_16x16x32_bf16 v[86:89], v[138:141], v[202:205], v[86:89]
	v_mfma_f32_16x16x32_bf16 v[78:81], v[130:133], v[218:221], v[78:81]
	v_mfma_f32_16x16x32_bf16 v[70:73], v[138:141], v[218:221], v[70:73]
	v_mfma_f32_16x16x32_bf16 v[114:117], v[134:137], v[190:193], v[114:117]
	v_mfma_f32_16x16x32_bf16 v[126:129], v[142:145], v[190:193], v[126:129]
	v_mfma_f32_16x16x32_bf16 v[110:113], v[134:137], v[198:201], v[110:113]
	v_mfma_f32_16x16x32_bf16 v[102:105], v[142:145], v[198:201], v[102:105]
	v_mfma_f32_16x16x32_bf16 v[94:97], v[134:137], v[206:209], v[94:97]
	v_mfma_f32_16x16x32_bf16 v[86:89], v[142:145], v[206:209], v[86:89]
	v_mfma_f32_16x16x32_bf16 v[78:81], v[134:137], v[222:225], v[78:81]
	v_mfma_f32_16x16x32_bf16 v[70:73], v[142:145], v[222:225], v[70:73]
	v_mfma_f32_16x16x32_bf16 v[122:125], v[146:149], v[186:189], v[122:125]
	v_mfma_f32_16x16x32_bf16 v[118:121], v[154:157], v[186:189], v[118:121]
	v_mfma_f32_16x16x32_bf16 v[106:109], v[146:149], v[194:197], v[106:109]
	v_mfma_f32_16x16x32_bf16 v[98:101], v[154:157], v[194:197], v[98:101]
	v_mfma_f32_16x16x32_bf16 v[90:93], v[146:149], v[202:205], v[90:93]
	v_mfma_f32_16x16x32_bf16 v[82:85], v[154:157], v[202:205], v[82:85]
	v_mfma_f32_16x16x32_bf16 v[74:77], v[146:149], v[218:221], v[74:77]
	v_mfma_f32_16x16x32_bf16 v[66:69], v[154:157], v[218:221], v[66:69]
	v_mfma_f32_16x16x32_bf16 v[122:125], v[150:153], v[190:193], v[122:125]
	v_mfma_f32_16x16x32_bf16 v[118:121], v[182:185], v[190:193], v[118:121]
	v_mfma_f32_16x16x32_bf16 v[106:109], v[150:153], v[198:201], v[106:109]
	v_mfma_f32_16x16x32_bf16 v[98:101], v[182:185], v[198:201], v[98:101]
	v_mfma_f32_16x16x32_bf16 v[90:93], v[150:153], v[206:209], v[90:93]
	v_mfma_f32_16x16x32_bf16 v[82:85], v[182:185], v[206:209], v[82:85]
	v_mfma_f32_16x16x32_bf16 v[74:77], v[150:153], v[222:225], v[74:77]
	v_mfma_f32_16x16x32_bf16 v[66:69], v[182:185], v[222:225], v[66:69]
	s_barrier
	s_add_i32 s17, s39, s70
	s_mov_b32 m0, s17
	ds_read_b128 v[186:189], v217 offset:16384
	ds_read_b128 v[190:193], v217 offset:17408
	ds_read_b128 v[194:197], v217 offset:18432
	ds_read_b128 v[198:201], v217 offset:19456
	ds_read_b128 v[202:205], v217 offset:20480
	ds_read_b128 v[206:209], v217 offset:21504
	ds_read_b128 v[218:221], v217 offset:22528
	ds_read_b128 v[222:225], v217 offset:23552
	global_load_lds_dwordx4 v160, s[40:41]
	s_add_i32 m0, s17, 0x2000
	s_add_i32 s17, s24, s70
	global_load_lds_dwordx4 v164, s[40:41]
	s_add_u32 s40, s40, s52
	s_addc_u32 s41, s41, s53
	s_mov_b32 m0, s17
	s_nop 0
	global_load_lds_dwordx4 v160, s[40:41]
	s_add_i32 m0, s17, 0x2000
	s_nop 0
	global_load_lds_dwordx4 v164, s[40:41]
	s_mov_b32 m0, s71
	s_nop 0
	global_load_lds_dwordx4 v158, s[2:3]
	s_mov_b32 m0, s34
	s_nop 0
	global_load_lds_dwordx4 v162, s[2:3]
	s_waitcnt vmcnt(8)
	s_waitcnt lgkmcnt(0)
	s_barrier
	v_mfma_f32_16x16x32_bf16 v[62:65], v[130:133], v[186:189], v[62:65]
	v_mfma_f32_16x16x32_bf16 v[54:57], v[138:141], v[186:189], v[54:57]
	v_mfma_f32_16x16x32_bf16 v[46:49], v[130:133], v[194:197], v[46:49]
	v_mfma_f32_16x16x32_bf16 v[38:41], v[138:141], v[194:197], v[38:41]
	v_mfma_f32_16x16x32_bf16 v[30:33], v[130:133], v[202:205], v[30:33]
	v_mfma_f32_16x16x32_bf16 v[22:25], v[138:141], v[202:205], v[22:25]
	v_mfma_f32_16x16x32_bf16 v[14:17], v[130:133], v[218:221], v[14:17]
	v_mfma_f32_16x16x32_bf16 v[6:9], v[138:141], v[218:221], v[6:9]
	v_mfma_f32_16x16x32_bf16 v[62:65], v[134:137], v[190:193], v[62:65]
	v_mfma_f32_16x16x32_bf16 v[54:57], v[142:145], v[190:193], v[54:57]
	v_mfma_f32_16x16x32_bf16 v[46:49], v[134:137], v[198:201], v[46:49]
	v_mfma_f32_16x16x32_bf16 v[38:41], v[142:145], v[198:201], v[38:41]
	v_mfma_f32_16x16x32_bf16 v[30:33], v[134:137], v[206:209], v[30:33]
	v_mfma_f32_16x16x32_bf16 v[22:25], v[142:145], v[206:209], v[22:25]
	v_mfma_f32_16x16x32_bf16 v[14:17], v[134:137], v[222:225], v[14:17]
	v_mfma_f32_16x16x32_bf16 v[6:9], v[142:145], v[222:225], v[6:9]
	v_mfma_f32_16x16x32_bf16 v[58:61], v[146:149], v[186:189], v[58:61]
	v_mfma_f32_16x16x32_bf16 v[50:53], v[154:157], v[186:189], v[50:53]
	v_mfma_f32_16x16x32_bf16 v[42:45], v[146:149], v[194:197], v[42:45]
	v_mfma_f32_16x16x32_bf16 v[34:37], v[154:157], v[194:197], v[34:37]
	v_mfma_f32_16x16x32_bf16 v[26:29], v[146:149], v[202:205], v[26:29]
	v_mfma_f32_16x16x32_bf16 v[18:21], v[154:157], v[202:205], v[18:21]
	v_mfma_f32_16x16x32_bf16 v[10:13], v[146:149], v[218:221], v[10:13]
	v_mfma_f32_16x16x32_bf16 v[2:5], v[154:157], v[218:221], v[2:5]
	v_mfma_f32_16x16x32_bf16 v[58:61], v[150:153], v[190:193], v[58:61]
	v_mfma_f32_16x16x32_bf16 v[50:53], v[182:185], v[190:193], v[50:53]
	v_mfma_f32_16x16x32_bf16 v[42:45], v[150:153], v[198:201], v[42:45]
	v_mfma_f32_16x16x32_bf16 v[34:37], v[182:185], v[198:201], v[34:37]
	v_mfma_f32_16x16x32_bf16 v[26:29], v[150:153], v[206:209], v[26:29]
	v_mfma_f32_16x16x32_bf16 v[18:21], v[182:185], v[206:209], v[18:21]
	v_mfma_f32_16x16x32_bf16 v[10:13], v[150:153], v[222:225], v[10:13]
	v_mfma_f32_16x16x32_bf16 v[2:5], v[182:185], v[222:225], v[2:5]
	s_barrier
; #define PG8_STAGE(bufoff, gbase, voff) do { _Pragma("unroll") for (int _i = 0; _i < 2; ++_i) \
;         __builtin_amdgcn_global_load_lds((const unsigned*)((const char*)(gbase) + (voff)[_i]), (LAS unsigned*)(lds + (bufoff) + ldsw + _i * 8192), 16, 0, 0); } while (0)
; #define PG8_LDA(dst, b, h) do { _Pragma("unroll") for (int m = 0; m < 4; ++m) _Pragma("unroll") for (int k = 0; k < 2; ++k) dst[m][k] = *(const LAS bf16x8*)(lds + PG8_SA(b, h) + aoff + m * 2048 + k * 1024); } while (0)
; #define PG8_LDB(dst, b, h) do { _Pragma("unroll") for (int n = 0; n < 2; ++n) _Pragma("unroll") for (int k = 0; k < 2; ++k) dst[n][k] = *(const LAS bf16x8*)(lds + PG8_SB(b, h) + boff + n * 2048 + k * 1024); } while (0)
; #define PG8_MMA(ai, bj, At, Bt) do { __builtin_amdgcn_s_setprio(1); _Pragma("unroll") for (int m = 0; m < 4; ++m) _Pragma("unroll") for (int n = 0; n < 2; ++n) _Pragma("unroll") for (int k = 0; k < 2; ++k) \
;         acc[ai][bj][m][n] = __builtin_amdgcn_mfma_f32_16x16x32_bf16(Bt[n][k], At[m][k], acc[ai][bj][m][n], 0, 0, 0); __builtin_amdgcn_s_setprio(0); } while (0)
; #define PG8_WAIT_V(n) asm volatile("s_waitcnt vmcnt(" #n ")" ::: "memory")
; #define PG8_WAIT_L(n) asm volatile("s_waitcnt lgkmcnt(" #n ")" ::: "memory")
; #define PG8_BAR __builtin_amdgcn_s_barrier()
; #define PG8_SCHED __builtin_amdgcn_sched_barrier(0)
; __device__ __forceinline__ void gemm_phase(LAS unsigned char* lds, const Gemm g, const StaticOrder& S, const Epi& E) {
;     ...
;             PG8_LDB(B0, 1, 0); PG8_LDB(B1, 1, 1); PG8_SCHED; PG8_LDA(At, 1, 0); PG8_STAGE(PG8_SA(0, 1), a2 + hstepA, voffA);
;             PG8_WAIT_V(8); PG8_WAIT_L(0); PG8_BAR; PG8_MMA(0, 0, At, B0); PG8_MMA(0, 1, At, B1); PG8_BAR; PG8_SCHED;
;             PG8_LDA(At, 1, 1); PG8_STAGE(PG8_SB(1, 0), b3, voffB); PG8_STAGE(PG8_SB(1, 1), b3 + hstepB, voffB); PG8_STAGE(PG8_SA(1, 0), a3, voffA);
;             PG8_WAIT_V(8); PG8_WAIT_L(0); PG8_BAR; PG8_MMA(1, 0, At, B0); PG8_MMA(1, 1, At, B1); PG8_BAR; PG8_SCHED;
	ds_read_b128 v[130:133], v228
	ds_read_b128 v[134:137], v228 offset:1024
	ds_read_b128 v[138:141], v228 offset:2048
	ds_read_b128 v[142:145], v228 offset:3072
	ds_read_b128 v[146:149], v229
	ds_read_b128 v[150:153], v229 offset:1024
	ds_read_b128 v[154:157], v229 offset:2048
	ds_read_b128 v[182:185], v229 offset:3072
	s_add_u32 s2, s2, s50
	s_addc_u32 s3, s3, s51
	s_mov_b32 m0, s92
	ds_read_b128 v[186:189], v217 offset:32768
	ds_read_b128 v[190:193], v217 offset:33792
	ds_read_b128 v[194:197], v217 offset:34816
	ds_read_b128 v[198:201], v217 offset:35840
	ds_read_b128 v[202:205], v217 offset:36864
	ds_read_b128 v[206:209], v217 offset:37888
	ds_read_b128 v[218:221], v217 offset:38912
	ds_read_b128 v[222:225], v217 offset:39936
	global_load_lds_dwordx4 v158, s[2:3]
	s_mov_b32 m0, s93
	s_nop 0
	global_load_lds_dwordx4 v162, s[2:3]
	s_waitcnt vmcnt(8)
	s_waitcnt lgkmcnt(0)
	s_barrier
	v_mfma_f32_16x16x32_bf16 v[114:117], v[130:133], v[186:189], v[114:117]
	v_mfma_f32_16x16x32_bf16 v[126:129], v[138:141], v[186:189], v[126:129]
	v_mfma_f32_16x16x32_bf16 v[110:113], v[130:133], v[194:197], v[110:113]
	v_mfma_f32_16x16x32_bf16 v[102:105], v[138:141], v[194:197], v[102:105]
	v_mfma_f32_16x16x32_bf16 v[94:97], v[130:133], v[202:205], v[94:97]
	v_mfma_f32_16x16x32_bf16 v[86:89], v[138:141], v[202:205], v[86:89]
	v_mfma_f32_16x16x32_bf16 v[78:81], v[130:133], v[218:221], v[78:81]
	v_mfma_f32_16x16x32_bf16 v[70:73], v[138:141], v[218:221], v[70:73]
	v_mfma_f32_16x16x32_bf16 v[114:117], v[134:137], v[190:193], v[114:117]
	v_mfma_f32_16x16x32_bf16 v[126:129], v[142:145], v[190:193], v[126:129]
	v_mfma_f32_16x16x32_bf16 v[110:113], v[134:137], v[198:201], v[110:113]
	v_mfma_f32_16x16x32_bf16 v[102:105], v[142:145], v[198:201], v[102:105]
	v_mfma_f32_16x16x32_bf16 v[94:97], v[134:137], v[206:209], v[94:97]
	v_mfma_f32_16x16x32_bf16 v[86:89], v[142:145], v[206:209], v[86:89]
	v_mfma_f32_16x16x32_bf16 v[78:81], v[134:137], v[222:225], v[78:81]
	v_mfma_f32_16x16x32_bf16 v[70:73], v[142:145], v[222:225], v[70:73]
	v_mfma_f32_16x16x32_bf16 v[122:125], v[146:149], v[186:189], v[122:125]
	v_mfma_f32_16x16x32_bf16 v[118:121], v[154:157], v[186:189], v[118:121]
	v_mfma_f32_16x16x32_bf16 v[106:109], v[146:149], v[194:197], v[106:109]
	v_mfma_f32_16x16x32_bf16 v[98:101], v[154:157], v[194:197], v[98:101]
	v_mfma_f32_16x16x32_bf16 v[90:93], v[146:149], v[202:205], v[90:93]
	v_mfma_f32_16x16x32_bf16 v[82:85], v[154:157], v[202:205], v[82:85]
	v_mfma_f32_16x16x32_bf16 v[74:77], v[146:149], v[218:221], v[74:77]
	v_mfma_f32_16x16x32_bf16 v[66:69], v[154:157], v[218:221], v[66:69]
	v_mfma_f32_16x16x32_bf16 v[122:125], v[150:153], v[190:193], v[122:125]
	v_mfma_f32_16x16x32_bf16 v[118:121], v[182:185], v[190:193], v[118:121]
	v_mfma_f32_16x16x32_bf16 v[106:109], v[150:153], v[198:201], v[106:109]
	v_mfma_f32_16x16x32_bf16 v[98:101], v[182:185], v[198:201], v[98:101]
	v_mfma_f32_16x16x32_bf16 v[90:93], v[150:153], v[206:209], v[90:93]
	v_mfma_f32_16x16x32_bf16 v[82:85], v[182:185], v[206:209], v[82:85]
	v_mfma_f32_16x16x32_bf16 v[74:77], v[150:153], v[222:225], v[74:77]
	v_mfma_f32_16x16x32_bf16 v[66:69], v[182:185], v[222:225], v[66:69]
	s_barrier
	s_add_u32 s40, s40, 0x80
	s_addc_u32 s41, s41, 0
	s_sub_u32 s100, s40, s52
	s_subb_u32 s101, s41, s53
	s_sub_u32 s2, s2, s50
	s_subb_u32 s3, s3, s51
	s_add_u32 s2, s2, 0x80
	s_addc_u32 s3, s3, 0
	s_add_i32 vcc_lo, s25, s70
	s_mov_b32 m0, vcc_lo
	ds_read_b128 v[186:189], v217 offset:49152
	ds_read_b128 v[190:193], v217 offset:50176
	ds_read_b128 v[194:197], v217 offset:51200
	ds_read_b128 v[198:201], v217 offset:52224
	ds_read_b128 v[202:205], v217 offset:53248
	ds_read_b128 v[206:209], v217 offset:54272
	ds_read_b128 v[218:221], v217 offset:55296
	ds_read_b128 v[222:225], v217 offset:56320
	global_load_lds_dwordx4 v160, s[100:101]
	s_add_i32 m0, vcc_lo, 0x2000
	s_add_i32 vcc_lo, s26, s70
	global_load_lds_dwordx4 v164, s[100:101]
	s_mov_b32 m0, vcc_lo
	s_nop 0
	global_load_lds_dwordx4 v160, s[40:41]
	s_add_i32 m0, vcc_lo, 0x2000
	s_nop 0
	global_load_lds_dwordx4 v164, s[40:41]
	s_mov_b32 m0, s58
	s_nop 0
	global_load_lds_dwordx4 v158, s[2:3]
	s_mov_b32 m0, s59
	s_nop 0
	global_load_lds_dwordx4 v162, s[2:3]
	s_waitcnt vmcnt(8)
	s_waitcnt lgkmcnt(0)
	s_barrier
	v_mfma_f32_16x16x32_bf16 v[62:65], v[130:133], v[186:189], v[62:65]
	v_mfma_f32_16x16x32_bf16 v[54:57], v[138:141], v[186:189], v[54:57]
	v_mfma_f32_16x16x32_bf16 v[46:49], v[130:133], v[194:197], v[46:49]
	v_mfma_f32_16x16x32_bf16 v[38:41], v[138:141], v[194:197], v[38:41]
	v_mfma_f32_16x16x32_bf16 v[30:33], v[130:133], v[202:205], v[30:33]
	v_mfma_f32_16x16x32_bf16 v[22:25], v[138:141], v[202:205], v[22:25]
	v_mfma_f32_16x16x32_bf16 v[14:17], v[130:133], v[218:221], v[14:17]
	v_mfma_f32_16x16x32_bf16 v[6:9], v[138:141], v[218:221], v[6:9]
	v_mfma_f32_16x16x32_bf16 v[62:65], v[134:137], v[190:193], v[62:65]
	v_mfma_f32_16x16x32_bf16 v[54:57], v[142:145], v[190:193], v[54:57]
	v_mfma_f32_16x16x32_bf16 v[46:49], v[134:137], v[198:201], v[46:49]
	v_mfma_f32_16x16x32_bf16 v[38:41], v[142:145], v[198:201], v[38:41]
	v_mfma_f32_16x16x32_bf16 v[30:33], v[134:137], v[206:209], v[30:33]
	v_mfma_f32_16x16x32_bf16 v[22:25], v[142:145], v[206:209], v[22:25]
	v_mfma_f32_16x16x32_bf16 v[14:17], v[134:137], v[222:225], v[14:17]
	v_mfma_f32_16x16x32_bf16 v[6:9], v[142:145], v[222:225], v[6:9]
	v_mfma_f32_16x16x32_bf16 v[58:61], v[146:149], v[186:189], v[58:61]
	v_mfma_f32_16x16x32_bf16 v[50:53], v[154:157], v[186:189], v[50:53]
	v_mfma_f32_16x16x32_bf16 v[42:45], v[146:149], v[194:197], v[42:45]
	v_mfma_f32_16x16x32_bf16 v[34:37], v[154:157], v[194:197], v[34:37]
	v_mfma_f32_16x16x32_bf16 v[26:29], v[146:149], v[202:205], v[26:29]
	v_mfma_f32_16x16x32_bf16 v[18:21], v[154:157], v[202:205], v[18:21]
	v_mfma_f32_16x16x32_bf16 v[10:13], v[146:149], v[218:221], v[10:13]
	v_mfma_f32_16x16x32_bf16 v[2:5], v[154:157], v[218:221], v[2:5]
	v_mfma_f32_16x16x32_bf16 v[58:61], v[150:153], v[190:193], v[58:61]
	v_mfma_f32_16x16x32_bf16 v[50:53], v[182:185], v[190:193], v[50:53]
	v_mfma_f32_16x16x32_bf16 v[42:45], v[150:153], v[198:201], v[42:45]
	v_mfma_f32_16x16x32_bf16 v[34:37], v[182:185], v[198:201], v[34:37]
	v_mfma_f32_16x16x32_bf16 v[26:29], v[150:153], v[206:209], v[26:29]
	v_mfma_f32_16x16x32_bf16 v[18:21], v[182:185], v[206:209], v[18:21]
	v_mfma_f32_16x16x32_bf16 v[10:13], v[150:153], v[222:225], v[10:13]
	v_mfma_f32_16x16x32_bf16 v[2:5], v[182:185], v[222:225], v[2:5]
	s_barrier
	s_add_u32 s0, s0, 0x100
	s_addc_u32 s1, s1, 0
	s_add_u32 s5, s5, 0x100
	s_addc_u32 s16, s16, 0
	s_cmp_ge_i32 s27, s84
	s_mov_b32 s17, s27
	s_cbranch_scc0 .LBB0_177
	s_and_b64 vcc, exec, s[74:75]
	s_cbranch_vccz .LBB0_180
